# forget-gate logits pre-step run at the start of the V^T GEMM position (no barrier before it) instead of the QK GEMM position, on top of v148
# speedup vs baseline: 1.0039x; 1.0039x over previous
; __device__ __forceinline__ int opaque_tid() { int t = threadIdx.x; asm volatile("" : "+v"(t)); return t; }
; __global__ void __launch_bounds__(NWAVES * 64, 2) fwd_megakernel(Args args) {
;     ...
;         if (j == 2) {
;             const int ln = opaque_tid() & 63;
;             float wreg[32];
; #pragma unroll
;             for (int jj = 0; jj < 4; ++jj) { const f32x4 a = *(const f32x4*)(wf + (size_t)wave * DM + 512 * jj + 8 * ln), bq = *(const f32x4*)(wf + (size_t)wave * DM + 512 * jj + 8 * ln + 4);
; #pragma unroll
;                 for (int e = 0; e < 4; ++e) { wreg[8 * jj + e] = a[e]; wreg[8 * jj + 4 + e] = bq[e]; } }
;             const float bf = args.in[8][wave];
;             for (int m0 = vcu2 * 4; m0 < M; m0 += G * 4) {
.LBB0_591:
	s_and_b64 vcc, exec, s[4:5]
	s_cbranch_vccz .LBB0_605
	s_cmp_gt_i32 s39, 1
	s_cbranch_scc0 .LBB0_606
	s_cmp_lt_i32 s39, 3
	s_mov_b64 s[4:5], -1
	s_cbranch_scc0 .LBB0_607
	s_branch .LBB0_608

; __device__ __forceinline__ int opaque_tid() { int t = threadIdx.x; asm volatile("" : "+v"(t)); return t; }
; __device__ __forceinline__ float rs_from_ss(float ss) { return rsqrtf(ss * (1.0f / DM) + RMS_EPS); }
; __global__ void __launch_bounds__(NWAVES * 64, 2) fwd_megakernel(Args args) {
;     ...
;         if (j == 2) {
;             const int ln = opaque_tid() & 63;
;             float wreg[32];
; #pragma unroll
;             for (int jj = 0; jj < 4; ++jj) { const f32x4 a = *(const f32x4*)(wf + (size_t)wave * DM + 512 * jj + 8 * ln), bq = *(const f32x4*)(wf + (size_t)wave * DM + 512 * jj + 8 * ln + 4);
; #pragma unroll
;                 for (int e = 0; e < 4; ++e) { wreg[8 * jj + e] = a[e]; wreg[8 * jj + 4 + e] = bq[e]; } }
;             const float bf = args.in[8][wave];
;             for (int m0 = vcu2 * 4; m0 < M; m0 += G * 4) {
;                 u32x4 pw[4][4]; float sq[4];
; #pragma unroll
;                 for (int q = 0; q < 4; ++q) { sq[q] = ss[M + m0 + q];
; #pragma unroll
;                     for (int jj = 0; jj < 4; ++jj) pw[q][jj] = *(const u32x4*)(XB + (size_t)(m0 + q) * DM + 512 * jj + 8 * ln); }
; #pragma unroll
;                 for (int q = 0; q < 4; ++q) { float d = 0.f;
; #pragma unroll
;                     for (int jj = 0; jj < 4; ++jj) { const u32x4 w = pw[q][jj];
;                         d += __uint_as_float(w.x << 16) * wreg[8 * jj + 0] + __uint_as_float(w.x & 0xffff0000u) * wreg[8 * jj + 1] + __uint_as_float(w.y << 16) * wreg[8 * jj + 2] + __uint_as_float(w.y & 0xffff0000u) * wreg[8 * jj + 3]
;                            + __uint_as_float(w.z << 16) * wreg[8 * jj + 4] + __uint_as_float(w.z & 0xffff0000u) * wreg[8 * jj + 5] + __uint_as_float(w.w << 16) * wreg[8 * jj + 6] + __uint_as_float(w.w & 0xffff0000u) * wreg[8 * jj + 7]; }
;                     d = wave_sum(d);
;                     if (ln == 0) { const int m = m0 + q; const float f = d * rs_from_ss(sq[q]) + bf; const float lf = fminf(f, 0.f) - log1pf(__expf(-fabsf(f)));
;                         logfb[((size_t)(m / SEQ) * NH + wave) * SEQ + (m % SEQ)] = lf; } }
;             }
.LBB0_607:
	s_cmp_lg_u32 s39, 3
	s_cbranch_scc1 .Llg_skip3
	s_mov_b64 s[98:99], s[8:9]
	v_lshrrev_b32_e32 v0, 6, v166
	v_readlane_b32 s4, v249, 1
	v_readfirstlane_b32 s12, v0
	s_lshl_b32 s4, s4, 4
	s_cmpk_gt_i32 s4, 0x3fff
	s_cbranch_scc1 .Llg_done
	v_lshlrev_b32_e32 v0, 4, v166
	s_add_u32 s8, s60, 0x100000
	s_addc_u32 s9, s61, 0
	global_load_dwordx4 v[36:39], v0, s[8:9]
	s_add_u32 s8, s8, 0x2000
	s_addc_u32 s9, s9, 0
	global_load_dwordx4 v[40:43], v0, s[8:9]
	s_add_u32 s8, s8, 0x2000
	s_addc_u32 s9, s9, 0
	global_load_dwordx4 v[44:47], v0, s[8:9]
	s_add_u32 s8, s8, 0x2000
	s_addc_u32 s9, s9, 0
	global_load_dwordx4 v[48:51], v0, s[8:9]
	s_add_u32 s8, s8, 0x2000
	s_addc_u32 s9, s9, 0
	global_load_dwordx4 v[52:55], v0, s[8:9]
	s_add_u32 s8, s8, 0x2000
	s_addc_u32 s9, s9, 0
	global_load_dwordx4 v[56:59], v0, s[8:9]
	s_add_u32 s8, s8, 0x2000
	s_addc_u32 s9, s9, 0
	global_load_dwordx4 v[60:63], v0, s[8:9]
	s_add_u32 s8, s8, 0x2000
	s_addc_u32 s9, s9, 0
	global_load_dwordx4 v[64:67], v0, s[8:9]
	v_lshrrev_b32_e32 v4, 5, v166
	v_lshlrev_b32_e32 v4, 12, v4
	v_and_b32_e32 v5, 1, v166
	v_lshl_or_b32 v4, v5, 10, v4
	v_bfe_u32 v5, v166, 1, 4
	v_lshl_or_b32 v4, v5, 6, v4
	v_and_b32_e32 v5, 3, v168
	v_lshrrev_b32_e32 v6, 2, v168
	v_lshlrev_b32_e32 v5, 12, v5
	v_lshl_or_b32 v2, v6, 4, v5
	v_lshlrev_b32_e32 v3, 4, v168
	v_add_u32_e32 v116, 0x4000, v2
	v_readlane_b32 s16, v250, 63
	v_readlane_b32 s17, v249, 0
	s_lshl_b32 s5, s12, 2
	s_sub_u32 s16, s16, s5
	s_subb_u32 s17, s17, 0
	s_mov_b32 s18, 0xbfb8aa3b
	s_mov_b32 s19, 0x3f317218
	s_waitcnt vmcnt(7)
	ds_write_b128 v4, v[36:39] offset:0
	s_waitcnt vmcnt(6)
	ds_write_b128 v4, v[40:43] offset:16
	s_waitcnt vmcnt(5)
	ds_write_b128 v4, v[44:47] offset:32
	s_waitcnt vmcnt(4)
	ds_write_b128 v4, v[48:51] offset:48
	s_waitcnt vmcnt(3)
	ds_write_b128 v4, v[52:55] offset:2048
	s_waitcnt vmcnt(2)
	ds_write_b128 v4, v[56:59] offset:2064
	s_waitcnt vmcnt(1)
	ds_write_b128 v4, v[60:63] offset:2080
	s_waitcnt vmcnt(0)
	ds_write_b128 v4, v[64:67] offset:2096
	s_waitcnt lgkmcnt(0)
	s_barrier

; __global__ void __launch_bounds__(NWAVES * 64, 2) fwd_megakernel(Args args) {
;     ...
;         }
.Llg_done:
	s_mov_b64 s[8:9], s[98:99]
	s_mov_b64 s[4:5], -1
